# u2 + dynamic last-two-rounds tile distribution in the up GEMM, pool size derived from the grid size at run time
# baseline (speedup 1.0000x reference)
;     __host__ __device__ bool next(int i, Unit& u) const {
;         const long L = (long)i * G + c; if (L >= nwg) return false;
.Ldq_have:
	s_mul_i32 s6, s14, 20
	s_sub_u32 s101, 0x1600, s6
	s_add_u32 s101, s101, s14
	s_lshl_b32 s100, s101, 1
	s_cmp_ge_u32 s99, s100
	s_cbranch_scc0 .Ldq_m1
	s_sub_u32 s99, s99, s100
.Ldq_m1:
	s_cmp_ge_u32 s99, s101
	s_cbranch_scc0 .Ldq_m2
	s_sub_u32 s99, s99, s101
.Ldq_m2:
	s_add_u32 s6, s6, s99
	s_mov_b32 s7, 0
	s_branch .Ldq_join
